# stack18: stack17 + hot loop heads (4 GEMM K-loops, attention loop) aligned to 64 bytes
# speedup vs baseline: 1.0089x; 1.0089x over previous
; #define WAIT_V0() asm volatile("s_waitcnt vmcnt(0)" ::: "memory")
; #define G_LANE_SETUP() \
;     int tid_ = threadIdx.x; \
;     asm volatile("" : "+v"(tid_));    \
;     const int wid = tid_ >> 6, lane = tid_ & 63, wr = wid >> 2, wc = wid & 3, fr = lane & 15, fq = lane >> 4; \
;     unsigned soff[4];        \
;     _Pragma("unroll") for (int i = 0; i < 4; ++i) { int sR, sC; stage_rc2(wid * 1024 + i * 8192 + lane * 16, sR, sC); soff[i] = (unsigned)(sR * K + sC) * 2u; }
; #define G_SB0() __builtin_amdgcn_sched_barrier(0)
; template <int EK>
; DI void gemm_stream(const Params& p, int l, const bf16_t* __restrict__ A, const bf16_t* __restrict__ Bt, int M, int N, int K, ldsp_t shm) {
;     ...
;     const int nt = K / 64;
;     int pm, pn;
;     tile_coords(L, nM, nN, pm, pn);
;     const bf16_t* Ab = A + (size_t)pm * 256 * K;
;     const bf16_t* Bb = Bt + (size_t)pn * 256 * K;
;     { G_LANE_SETUP(); (void)wr; (void)wc; (void)fr; (void)fq; G_STAGE(Ab, Bb, 0, 0); WAIT_V0(); __syncthreads(); }
;     while (true) {
;         G_LANE_SETUP();
;         const int aoff = lds_byte2(wr * 128 + fr, fq * 8), boff = lds_byte2(wc * 64 + fr, fq * 8);
;         f32x4 acc[8][4];
; #pragma unroll
;         for (int m = 0; m < 8; ++m)
; #pragma unroll
;             for (int n = 0; n < 4; ++n) acc[m][n] = (f32x4){0.f, 0.f, 0.f, 0.f};
;         const int Ln = L + gridDim.x;
;         const bool has_next = Ln < nwg;
;         int pm2 = pm, pn2 = pn;
;         if (has_next) tile_coords(Ln, nM, nN, pm2, pn2);
;         const bf16_t* Ab2 = A + (size_t)pm2 * 256 * K;
;         const bf16_t* Bb2 = Bt + (size_t)pn2 * 256 * K;
;         bf16x8 Aa[4], Ab_[4], Bk0[4], Bk1[4];
;     ...
;         for (int t = 0; t < nt; ++t) {
;             const int cur = t & 1;
;             G_RDA(Aa, cur, 0, 0); G_RDB(Bk0, cur, 0);
;             if (t + 1 < nt) G_STAGE_B(Bb, cur ^ 1, t + 1);
;             else if (has_next) G_STAGE_B(Bb2, cur ^ 1, 0);
;             G_SB0();
;             if (t > 0) G_MMA(Ab_, Bk1, 1);
;             G_SB0();
;             if (t + 1 < nt) G_STAGE_A(Ab, cur ^ 1, t + 1);
;             else if (has_next) G_STAGE_A(Ab2, cur ^ 1, 0);
;             G_RDA(Ab_, cur, 0, 1);
;             G_MMA(Aa, Bk0, 0); G_SB0();
;             G_RDA(Aa, cur, 1, 0); G_RDB(Bk1, cur, 1);
;             G_MMA(Ab_, Bk0, 1); G_SB0();
;             G_RDA(Ab_, cur, 1, 1);
;             G_MMA(Aa, Bk1, 0); G_SB0();
.LBB0_110:
	v_lshlrev_b32_e32 v0, 4, v160
	v_and_b32_e32 v1, 32, v160
	v_bfe_u32 v161, v160, 2, 4
	v_and_b32_e32 v190, 64, v160
	v_bitop3_b32 v191, v0, v1, 48 bitop3:0x6c
	v_lshrrev_b32_e32 v2, 3, v160
	v_or_b32_e32 v1, v191, v190
	v_and_or_b32 v2, v2, s86, v161
	v_add_u32_e32 v200, 0x2000, v0
	v_lshl_or_b32 v192, v2, 11, v1
	v_lshrrev_b32_e32 v2, 7, v200
	v_and_or_b32 v2, v2, s86, v161
	v_add_u32_e32 v201, 0x4000, v0
	v_add_u32_e32 v221, 0x6000, v0
	v_and_b32_e32 v220, 0xfffffc00, v0
	v_lshl_or_b32 v194, v2, 11, v1
	v_lshrrev_b32_e32 v2, 7, v201
	v_lshrrev_b32_e32 v0, 7, v221
	v_and_or_b32 v2, v2, s86, v161
	v_and_or_b32 v0, v0, s86, v161
	v_lshl_or_b32 v196, v2, 11, v1
	v_lshl_or_b32 v198, v0, 11, v1
	v_lshlrev_b32_e32 v1, 6, v160
	v_lshlrev_b32_e32 v4, 2, v160
	v_and_b32_e32 v0, 48, v160
	v_and_b32_e32 v2, 0x3c0, v1
	v_and_b32_e32 v4, 32, v4
	v_bitop3_b32 v0, v2, v4, v0 bitop3:0x36
	s_movk_i32 s4, 0xc000
	v_and_or_b32 v218, v1, s4, v0
	s_add_u32 s4, s9, s38
	s_addc_u32 s5, s45, s39
	v_add_u32_e32 v34, 0x18000, v220
	v_lshl_add_u64 v[32:33], s[4:5], 0, v[192:193]
	v_readfirstlane_b32 s35, v34
	v_lshlrev_b32_e32 v3, 7, v160
	v_lshl_add_u64 v[32:33], v[32:33], 0, s[0:1]
	s_mov_b32 m0, s35
	v_mov_b32_e32 v195, v193
	v_add_u32_e32 v34, 0x1a000, v220
	v_and_or_b32 v219, v3, s28, v0
	ds_read_b128 v[0:3], v218
	ds_read_b128 v[4:7], v218 offset:2048
	ds_read_b128 v[8:11], v218 offset:4096
	ds_read_b128 v[12:15], v218 offset:6144
	ds_read_b128 v[16:19], v219 offset:32768
	ds_read_b128 v[20:23], v219 offset:34816
	ds_read_b128 v[24:27], v219 offset:36864
	ds_read_b128 v[28:31], v219 offset:38912
	global_load_lds_dwordx4 v[32:33], off
	v_lshl_add_u64 v[32:33], s[4:5], 0, v[194:195]
	v_readfirstlane_b32 s35, v34
	v_lshl_add_u64 v[32:33], v[32:33], 0, s[0:1]
	s_mov_b32 m0, s35
	v_mov_b32_e32 v197, v193
	v_add_u32_e32 v34, 0x1c000, v220
	global_load_lds_dwordx4 v[32:33], off
	v_lshl_add_u64 v[32:33], s[4:5], 0, v[196:197]
	v_readfirstlane_b32 s35, v34
	v_lshl_add_u64 v[32:33], v[32:33], 0, s[0:1]
	s_mov_b32 m0, s35
	v_mov_b32_e32 v199, v193
	v_add_u32_e32 v34, 0x1e000, v220
	global_load_lds_dwordx4 v[32:33], off
	v_lshl_add_u64 v[32:33], s[4:5], 0, v[198:199]
	v_readfirstlane_b32 s4, v34
	v_lshl_add_u64 v[32:33], v[32:33], 0, s[0:1]
	s_mov_b32 m0, s4
	s_nop 0
	global_load_lds_dwordx4 v[32:33], off
	s_add_u32 s4, s82, s40
	s_addc_u32 s5, s83, s41
	v_add_u32_e32 v34, 0x10000, v220
	v_lshl_add_u64 v[32:33], s[4:5], 0, v[192:193]
	v_readfirstlane_b32 s35, v34
	v_lshl_add_u64 v[32:33], v[32:33], 0, s[0:1]
	s_mov_b32 m0, s35
	v_add_u32_e32 v34, 0x12000, v220
	global_load_lds_dwordx4 v[32:33], off
	v_lshl_add_u64 v[32:33], s[4:5], 0, v[194:195]
	v_readfirstlane_b32 s35, v34
	v_lshl_add_u64 v[32:33], v[32:33], 0, s[0:1]
	s_mov_b32 m0, s35
	v_add_u32_e32 v34, 0x14000, v220
	global_load_lds_dwordx4 v[32:33], off
	v_lshl_add_u64 v[32:33], s[4:5], 0, v[196:197]
	v_readfirstlane_b32 s35, v34
	v_lshl_add_u64 v[32:33], v[32:33], 0, s[0:1]
	s_mov_b32 m0, s35
	v_add_u32_e32 v34, 0x16000, v220
	global_load_lds_dwordx4 v[32:33], off
	v_lshl_add_u64 v[32:33], s[4:5], 0, v[198:199]
	v_readfirstlane_b32 s4, v34
	v_lshl_add_u64 v[32:33], v[32:33], 0, s[0:1]
	s_mov_b32 m0, s4
	s_mov_b32 s35, 0x10000
	global_load_lds_dwordx4 v[32:33], off
	ds_read_b128 v[32:35], v218 offset:8192
	ds_read_b128 v[36:39], v218 offset:10240
	ds_read_b128 v[40:43], v218 offset:12288
	ds_read_b128 v[44:47], v218 offset:14336
	s_setprio 1
	s_waitcnt lgkmcnt(0)
; #define WAIT_V0() asm volatile("s_waitcnt vmcnt(0)" ::: "memory")
; #define G_STAGE_A(Ap, buf, kt) do { const char* ab_ = (const char*)(Ap) + (size_t)(kt) * 128; \
;       _Pragma("unroll") for (int i = 0; i < 4; ++i) \
;         __builtin_amdgcn_global_load_lds((const unsigned*)(ab_ + soff[i]), (LDSP unsigned*)(G_SA(buf) + wid * 1024 + i * 8192), 16, 0, 0); } while (0)
; #define G_STAGE_B(Bp, buf, kt) do { const char* bb_ = (const char*)(Bp) + (size_t)(kt) * 128; \
;       _Pragma("unroll") for (int i = 0; i < 4; ++i) \
;         __builtin_amdgcn_global_load_lds((const unsigned*)(bb_ + soff[i]), (LDSP unsigned*)(G_SB(buf) + wid * 1024 + i * 8192), 16, 0, 0); } while (0)
; #define G_RDA(AF, buf, ks, mh) do { _Pragma("unroll") for (int m = 0; m < 4; ++m) AF[m] = *(const LDSP bf16x8*)(G_SA(buf) + aoff + ((mh) * 4 + m) * 2048 + (ks) * 1024); } while (0)
; #define G_RDB(BF, buf, ks) do { _Pragma("unroll") for (int n = 0; n < 4; ++n) BF[n] = *(const LDSP bf16x8*)(G_SB(buf) + boff + n * 2048 + (ks) * 1024); } while (0)
; #define G_MMA(AF, BF, mh) do { __builtin_amdgcn_s_setprio(1); \
;             _Pragma("unroll") for (int m = 0; m < 4; ++m) _Pragma("unroll") for (int n = 0; n < 4; ++n) \
;                 acc[(mh) * 4 + m][n] = __builtin_amdgcn_mfma_f32_16x16x32_bf16(BF[n], AF[m], acc[(mh) * 4 + m][n], 0, 0, 0); \
;             __builtin_amdgcn_s_setprio(0); } while (0)
; template <int EK>
; DI void gemm_stream(const Params& p, int l, const bf16_t* __restrict__ A, const bf16_t* __restrict__ Bt, int M, int N, int K, ldsp_t shm) {
;     ...
;         for (int t = 0; t < nt; ++t) {
;             const int cur = t & 1;
;             G_RDA(Aa, cur, 0, 0); G_RDB(Bk0, cur, 0);
;             if (t + 1 < nt) G_STAGE_B(Bb, cur ^ 1, t + 1);
;             else if (has_next) G_STAGE_B(Bb2, cur ^ 1, 0);
;             G_SB0();
;             if (t > 0) G_MMA(Ab_, Bk1, 1);
;             G_SB0();
;             if (t + 1 < nt) G_STAGE_A(Ab, cur ^ 1, t + 1);
;             else if (has_next) G_STAGE_A(Ab2, cur ^ 1, 0);
;             G_RDA(Ab_, cur, 0, 1);
;             G_MMA(Aa, Bk0, 0); G_SB0();
;             G_RDA(Aa, cur, 1, 0); G_RDB(Bk1, cur, 1);
;             G_MMA(Ab_, Bk0, 1); G_SB0();
;             G_RDA(Ab_, cur, 1, 1);
;             G_MMA(Aa, Bk1, 0); G_SB0();
;             asm volatile("s_waitcnt lgkmcnt(0)" ::: "memory");
;             WAIT_V0(); __syncthreads();
;         }
	v_mfma_f32_16x16x32_bf16 v[48:51], v[16:19], v[0:3], 0
	v_mfma_f32_16x16x32_bf16 v[52:55], v[20:23], v[0:3], 0
	v_mfma_f32_16x16x32_bf16 v[162:165], v[24:27], v[0:3], 0
	v_mfma_f32_16x16x32_bf16 v[0:3], v[28:31], v[0:3], 0
	v_mfma_f32_16x16x32_bf16 v[166:169], v[16:19], v[4:7], 0
	v_mfma_f32_16x16x32_bf16 v[170:173], v[20:23], v[4:7], 0
	v_mfma_f32_16x16x32_bf16 v[174:177], v[24:27], v[4:7], 0
	v_mfma_f32_16x16x32_bf16 v[4:7], v[28:31], v[4:7], 0
	v_mfma_f32_16x16x32_bf16 v[178:181], v[16:19], v[8:11], 0
	v_mfma_f32_16x16x32_bf16 v[182:185], v[20:23], v[8:11], 0
	v_mfma_f32_16x16x32_bf16 v[186:189], v[24:27], v[8:11], 0
	v_mfma_f32_16x16x32_bf16 v[8:11], v[28:31], v[8:11], 0
	v_mfma_f32_16x16x32_bf16 v[204:207], v[16:19], v[12:15], 0
	v_mfma_f32_16x16x32_bf16 v[210:213], v[20:23], v[12:15], 0
	v_mfma_f32_16x16x32_bf16 v[214:217], v[24:27], v[12:15], 0
	v_mfma_f32_16x16x32_bf16 v[222:225], v[28:31], v[12:15], 0
	s_setprio 0
	ds_read_b128 v[12:15], v218 offset:1024
	ds_read_b128 v[226:229], v218 offset:3072
	ds_read_b128 v[230:233], v218 offset:5120
	ds_read_b128 v[234:237], v218 offset:7168
	ds_read_b128 v[64:67], v219 offset:33792
	ds_read_b128 v[68:71], v219 offset:35840
	ds_read_b128 v[76:79], v219 offset:37888
	ds_read_b128 v[72:75], v219 offset:39936
	s_setprio 1
	v_mfma_f32_16x16x32_bf16 v[128:131], v[16:19], v[32:35], 0
	v_mfma_f32_16x16x32_bf16 v[124:127], v[20:23], v[32:35], 0
	v_mfma_f32_16x16x32_bf16 v[120:123], v[24:27], v[32:35], 0
	v_mfma_f32_16x16x32_bf16 v[116:119], v[28:31], v[32:35], 0
	v_mfma_f32_16x16x32_bf16 v[112:115], v[16:19], v[36:39], 0
	v_mfma_f32_16x16x32_bf16 v[108:111], v[20:23], v[36:39], 0
	v_mfma_f32_16x16x32_bf16 v[104:107], v[24:27], v[36:39], 0
	v_mfma_f32_16x16x32_bf16 v[100:103], v[28:31], v[36:39], 0
	v_mfma_f32_16x16x32_bf16 v[96:99], v[16:19], v[40:43], 0
	v_mfma_f32_16x16x32_bf16 v[92:95], v[20:23], v[40:43], 0
	v_mfma_f32_16x16x32_bf16 v[88:91], v[24:27], v[40:43], 0
	v_mfma_f32_16x16x32_bf16 v[84:87], v[28:31], v[40:43], 0
	v_mfma_f32_16x16x32_bf16 v[132:135], v[16:19], v[44:47], 0
	v_mfma_f32_16x16x32_bf16 v[136:139], v[20:23], v[44:47], 0
	v_mfma_f32_16x16x32_bf16 v[140:143], v[24:27], v[44:47], 0
	v_mfma_f32_16x16x32_bf16 v[80:83], v[28:31], v[44:47], 0
	s_setprio 0
	ds_read_b128 v[156:159], v218 offset:9216
	ds_read_b128 v[152:155], v218 offset:11264
	ds_read_b128 v[148:151], v218 offset:13312
	ds_read_b128 v[144:147], v218 offset:15360
	s_setprio 1
	s_waitcnt lgkmcnt(0)
	v_mfma_f32_16x16x32_bf16 v[60:63], v[64:67], v[12:15], v[48:51]
	v_mfma_f32_16x16x32_bf16 v[56:59], v[68:71], v[12:15], v[52:55]
	v_mfma_f32_16x16x32_bf16 v[52:55], v[76:79], v[12:15], v[162:165]
	v_mfma_f32_16x16x32_bf16 v[48:51], v[72:75], v[12:15], v[0:3]
	v_mfma_f32_16x16x32_bf16 v[44:47], v[64:67], v[226:229], v[166:169]
	v_mfma_f32_16x16x32_bf16 v[40:43], v[68:71], v[226:229], v[170:173]
	v_mfma_f32_16x16x32_bf16 v[36:39], v[76:79], v[226:229], v[174:177]
	v_mfma_f32_16x16x32_bf16 v[32:35], v[72:75], v[226:229], v[4:7]
	v_mfma_f32_16x16x32_bf16 v[28:31], v[64:67], v[230:233], v[178:181]
	v_mfma_f32_16x16x32_bf16 v[24:27], v[68:71], v[230:233], v[182:185]
	v_mfma_f32_16x16x32_bf16 v[20:23], v[76:79], v[230:233], v[186:189]
	v_mfma_f32_16x16x32_bf16 v[16:19], v[72:75], v[230:233], v[8:11]
	v_mfma_f32_16x16x32_bf16 v[12:15], v[64:67], v[234:237], v[204:207]
	v_mfma_f32_16x16x32_bf16 v[8:11], v[68:71], v[234:237], v[210:213]
	v_mfma_f32_16x16x32_bf16 v[4:7], v[76:79], v[234:237], v[214:217]
	v_mfma_f32_16x16x32_bf16 v[0:3], v[72:75], v[234:237], v[222:225]
	s_setprio 0
	v_lshlrev_b32_e32 v160, 8, v160
	v_lshlrev_b32_e32 v162, 4, v200
	v_lshlrev_b32_e32 v164, 4, v201
	v_lshlrev_b32_e32 v167, 4, v221
	v_and_or_b32 v160, v160, s90, v191
	v_lshlrev_b32_e32 v166, 11, v161
	s_add_u32 s4, s31, s38
	v_and_or_b32 v162, v162, s90, v191
	v_and_or_b32 v164, v164, s90, v191
	v_and_or_b32 v167, v167, s90, v191
	v_or3_b32 v168, v160, v166, v190
	v_mov_b32_e32 v169, v193
	s_addc_u32 s5, s46, s39
	v_or3_b32 v170, v162, v166, v190
	v_mov_b32_e32 v171, v193
	v_or3_b32 v172, v164, v166, v190
	v_mov_b32_e32 v173, v193
	v_or3_b32 v174, v167, v166, v190
	v_mov_b32_e32 v175, v193
	s_waitcnt lgkmcnt(0)
	v_writelane_b32 v255, s52, 12
	v_writelane_b32 v255, s53, 13
	v_writelane_b32 v255, s64, 14
	v_writelane_b32 v255, s65, 15
	v_writelane_b32 v255, s30, 16
	s_mov_b64 s[64:65], s[4:5]
	v_readlane_b32 s4, v254, 18
	s_waitcnt vmcnt(0)
	s_add_u32 s4, s4, s40
	v_readlane_b32 s5, v254, 19
	s_addc_u32 s5, s5, s41
	s_waitcnt vmcnt(0)
	s_mov_b64 s[52:53], s[4:5]
	s_mov_b64 s[4:5], 0
	v_lshrrev_b32_e32 v164, 6, v252
	v_lshlrev_b32_e32 v164, 10, v164
	s_nop 0
	v_readfirstlane_b32 s30, v164
	v_and_b32_e32 v165, 63, v252
	v_lshlrev_b32_e32 v165, 4, v165
	s_barrier
	s_and_b32 s37, s35, 0x10000
	v_add_u32_e32 v221, s37, v218
	v_or_b32_e32 v226, s37, v219
	s_xor_b32 s37, s37, 0x10000
	s_add_u32 s37, s37, s30
	.p2align	6

; #define WAIT_V0() asm volatile("s_waitcnt vmcnt(0)" ::: "memory")
; #define G_LANE_SETUP() \
;     int tid_ = threadIdx.x; \
;     asm volatile("" : "+v"(tid_));    \
;     const int wid = tid_ >> 6, lane = tid_ & 63, wr = wid >> 2, wc = wid & 3, fr = lane & 15, fq = lane >> 4; \
;     unsigned soff[4];        \
;     _Pragma("unroll") for (int i = 0; i < 4; ++i) { int sR, sC; stage_rc2(wid * 1024 + i * 8192 + lane * 16, sR, sC); soff[i] = (unsigned)(sR * K + sC) * 2u; }
; #define G_SB0() __builtin_amdgcn_sched_barrier(0)
; template <int EK>
; DI void gemm_stream(const Params& p, int l, const bf16_t* __restrict__ A, const bf16_t* __restrict__ Bt, int M, int N, int K, ldsp_t shm) {
;     ...
;     const int nt = K / 64;
;     int pm, pn;
;     tile_coords(L, nM, nN, pm, pn);
;     const bf16_t* Ab = A + (size_t)pm * 256 * K;
;     const bf16_t* Bb = Bt + (size_t)pn * 256 * K;
;     { G_LANE_SETUP(); (void)wr; (void)wc; (void)fr; (void)fq; G_STAGE(Ab, Bb, 0, 0); WAIT_V0(); __syncthreads(); }
;     while (true) {
;         G_LANE_SETUP();
;         const int aoff = lds_byte2(wr * 128 + fr, fq * 8), boff = lds_byte2(wc * 64 + fr, fq * 8);
;         f32x4 acc[8][4];
; #pragma unroll
;         for (int m = 0; m < 8; ++m)
; #pragma unroll
;             for (int n = 0; n < 4; ++n) acc[m][n] = (f32x4){0.f, 0.f, 0.f, 0.f};
;         const int Ln = L + gridDim.x;
;         const bool has_next = Ln < nwg;
;         int pm2 = pm, pn2 = pn;
;         if (has_next) tile_coords(Ln, nM, nN, pm2, pn2);
;         const bf16_t* Ab2 = A + (size_t)pm2 * 256 * K;
;         const bf16_t* Bb2 = Bt + (size_t)pn2 * 256 * K;
;         bf16x8 Aa[4], Ab_[4], Bk0[4], Bk1[4];
;     ...
;         for (int t = 0; t < nt; ++t) {
;             const int cur = t & 1;
;             G_RDA(Aa, cur, 0, 0); G_RDB(Bk0, cur, 0);
;             if (t + 1 < nt) G_STAGE_B(Bb, cur ^ 1, t + 1);
;             else if (has_next) G_STAGE_B(Bb2, cur ^ 1, 0);
;             G_SB0();
;             if (t > 0) G_MMA(Ab_, Bk1, 1);
;             G_SB0();
;             if (t + 1 < nt) G_STAGE_A(Ab, cur ^ 1, t + 1);
;             else if (has_next) G_STAGE_A(Ab2, cur ^ 1, 0);
;             G_RDA(Ab_, cur, 0, 1);
;             G_MMA(Aa, Bk0, 0); G_SB0();
;             G_RDA(Aa, cur, 1, 0); G_RDB(Bk1, cur, 1);
;             G_MMA(Ab_, Bk0, 1); G_SB0();
;             G_RDA(Ab_, cur, 1, 1);
;             G_MMA(Aa, Bk1, 0); G_SB0();
.LBB0_131:
	v_lshlrev_b32_e32 v0, 4, v160
	v_and_b32_e32 v1, 32, v160
	v_bfe_u32 v161, v160, 2, 4
	v_and_b32_e32 v190, 64, v160
	v_bitop3_b32 v191, v0, v1, 48 bitop3:0x6c
	v_lshrrev_b32_e32 v2, 3, v160
	s_mov_b32 s6, 0x1ffff0
	v_or_b32_e32 v1, v191, v190
	v_and_or_b32 v2, v2, s6, v161
	v_add_u32_e32 v200, 0x2000, v0
	v_lshl_or_b32 v192, v2, 11, v1
	v_lshrrev_b32_e32 v2, 7, v200
	v_and_or_b32 v2, v2, s6, v161
	v_add_u32_e32 v201, 0x4000, v0
	v_add_u32_e32 v221, 0x6000, v0
	v_and_b32_e32 v220, 0xfffffc00, v0
	v_lshl_or_b32 v194, v2, 11, v1
	v_lshrrev_b32_e32 v2, 7, v201
	v_lshrrev_b32_e32 v0, 7, v221
	v_and_or_b32 v2, v2, s6, v161
	v_and_or_b32 v0, v0, s6, v161
	v_lshl_or_b32 v196, v2, 11, v1
	v_lshl_or_b32 v198, v0, 11, v1
	v_lshlrev_b32_e32 v1, 6, v160
	v_lshlrev_b32_e32 v4, 2, v160
	v_and_b32_e32 v0, 48, v160
	v_and_b32_e32 v2, 0x3c0, v1
	v_and_b32_e32 v4, 32, v4
	v_bitop3_b32 v0, v2, v4, v0 bitop3:0x36
	s_movk_i32 s6, 0xc000
	v_and_or_b32 v218, v1, s6, v0
	s_add_u32 s6, s93, s46
	s_addc_u32 s7, s98, s47
	v_add_u32_e32 v34, 0x18000, v220
	v_lshl_add_u64 v[32:33], s[6:7], 0, v[192:193]
	v_readfirstlane_b32 s41, v34
	v_lshlrev_b32_e32 v3, 7, v160
	v_lshl_add_u64 v[32:33], v[32:33], 0, s[0:1]
	s_mov_b32 m0, s41
	v_mov_b32_e32 v195, v193
	v_add_u32_e32 v34, 0x1a000, v220
	v_and_or_b32 v219, v3, s28, v0
	ds_read_b128 v[0:3], v218
	ds_read_b128 v[4:7], v218 offset:2048
	ds_read_b128 v[8:11], v218 offset:4096
	ds_read_b128 v[12:15], v218 offset:6144
	ds_read_b128 v[16:19], v219 offset:32768
	ds_read_b128 v[20:23], v219 offset:34816
	ds_read_b128 v[24:27], v219 offset:36864
	ds_read_b128 v[28:31], v219 offset:38912
	global_load_lds_dwordx4 v[32:33], off
	v_lshl_add_u64 v[32:33], s[6:7], 0, v[194:195]
	v_readfirstlane_b32 s41, v34
	v_lshl_add_u64 v[32:33], v[32:33], 0, s[0:1]
	s_mov_b32 m0, s41
	v_mov_b32_e32 v197, v193
	v_add_u32_e32 v34, 0x1c000, v220
	global_load_lds_dwordx4 v[32:33], off
	v_lshl_add_u64 v[32:33], s[6:7], 0, v[196:197]
	v_readfirstlane_b32 s41, v34
	v_lshl_add_u64 v[32:33], v[32:33], 0, s[0:1]
	s_mov_b32 m0, s41
	v_mov_b32_e32 v199, v193
	v_add_u32_e32 v34, 0x1e000, v220
	global_load_lds_dwordx4 v[32:33], off
	v_lshl_add_u64 v[32:33], s[6:7], 0, v[198:199]
	v_readfirstlane_b32 s6, v34
	v_lshl_add_u64 v[32:33], v[32:33], 0, s[0:1]
	s_mov_b32 m0, s6
	s_nop 0
	global_load_lds_dwordx4 v[32:33], off
	s_add_u32 s6, s26, s50
	s_addc_u32 s7, s27, s51
	v_add_u32_e32 v34, 0x10000, v220
	v_lshl_add_u64 v[32:33], s[6:7], 0, v[192:193]
	v_readfirstlane_b32 s41, v34
	v_lshl_add_u64 v[32:33], v[32:33], 0, s[0:1]
	s_mov_b32 m0, s41
	v_add_u32_e32 v34, 0x12000, v220
	global_load_lds_dwordx4 v[32:33], off
	v_lshl_add_u64 v[32:33], s[6:7], 0, v[194:195]
	v_readfirstlane_b32 s41, v34
	v_lshl_add_u64 v[32:33], v[32:33], 0, s[0:1]
	s_mov_b32 m0, s41
	v_add_u32_e32 v34, 0x14000, v220
	global_load_lds_dwordx4 v[32:33], off
	v_lshl_add_u64 v[32:33], s[6:7], 0, v[196:197]
	v_readfirstlane_b32 s41, v34
	v_lshl_add_u64 v[32:33], v[32:33], 0, s[0:1]
	s_mov_b32 m0, s41
	v_add_u32_e32 v34, 0x16000, v220
	global_load_lds_dwordx4 v[32:33], off
	v_lshl_add_u64 v[32:33], s[6:7], 0, v[198:199]
	v_readfirstlane_b32 s6, v34
	v_lshl_add_u64 v[32:33], v[32:33], 0, s[0:1]
	s_mov_b32 m0, s6
	s_mov_b32 s41, 0x10000
	global_load_lds_dwordx4 v[32:33], off
	ds_read_b128 v[32:35], v218 offset:8192
	ds_read_b128 v[36:39], v218 offset:10240
	ds_read_b128 v[40:43], v218 offset:12288
	ds_read_b128 v[44:47], v218 offset:14336
	s_setprio 1
	s_waitcnt lgkmcnt(0)
; #define WAIT_V0() asm volatile("s_waitcnt vmcnt(0)" ::: "memory")
; #define G_STAGE_A(Ap, buf, kt) do { const char* ab_ = (const char*)(Ap) + (size_t)(kt) * 128; \
;       _Pragma("unroll") for (int i = 0; i < 4; ++i) \
;         __builtin_amdgcn_global_load_lds((const unsigned*)(ab_ + soff[i]), (LDSP unsigned*)(G_SA(buf) + wid * 1024 + i * 8192), 16, 0, 0); } while (0)
; #define G_STAGE_B(Bp, buf, kt) do { const char* bb_ = (const char*)(Bp) + (size_t)(kt) * 128; \
;       _Pragma("unroll") for (int i = 0; i < 4; ++i) \
;         __builtin_amdgcn_global_load_lds((const unsigned*)(bb_ + soff[i]), (LDSP unsigned*)(G_SB(buf) + wid * 1024 + i * 8192), 16, 0, 0); } while (0)
; #define G_RDA(AF, buf, ks, mh) do { _Pragma("unroll") for (int m = 0; m < 4; ++m) AF[m] = *(const LDSP bf16x8*)(G_SA(buf) + aoff + ((mh) * 4 + m) * 2048 + (ks) * 1024); } while (0)
; #define G_RDB(BF, buf, ks) do { _Pragma("unroll") for (int n = 0; n < 4; ++n) BF[n] = *(const LDSP bf16x8*)(G_SB(buf) + boff + n * 2048 + (ks) * 1024); } while (0)
; #define G_MMA(AF, BF, mh) do { __builtin_amdgcn_s_setprio(1); \
;             _Pragma("unroll") for (int m = 0; m < 4; ++m) _Pragma("unroll") for (int n = 0; n < 4; ++n) \
;                 acc[(mh) * 4 + m][n] = __builtin_amdgcn_mfma_f32_16x16x32_bf16(BF[n], AF[m], acc[(mh) * 4 + m][n], 0, 0, 0); \
;             __builtin_amdgcn_s_setprio(0); } while (0)
; template <int EK>
; DI void gemm_stream(const Params& p, int l, const bf16_t* __restrict__ A, const bf16_t* __restrict__ Bt, int M, int N, int K, ldsp_t shm) {
;     ...
;         for (int t = 0; t < nt; ++t) {
;             const int cur = t & 1;
;             G_RDA(Aa, cur, 0, 0); G_RDB(Bk0, cur, 0);
;             if (t + 1 < nt) G_STAGE_B(Bb, cur ^ 1, t + 1);
;             else if (has_next) G_STAGE_B(Bb2, cur ^ 1, 0);
;             G_SB0();
;             if (t > 0) G_MMA(Ab_, Bk1, 1);
;             G_SB0();
;             if (t + 1 < nt) G_STAGE_A(Ab, cur ^ 1, t + 1);
;             else if (has_next) G_STAGE_A(Ab2, cur ^ 1, 0);
;             G_RDA(Ab_, cur, 0, 1);
;             G_MMA(Aa, Bk0, 0); G_SB0();
;             G_RDA(Aa, cur, 1, 0); G_RDB(Bk1, cur, 1);
;             G_MMA(Ab_, Bk0, 1); G_SB0();
;             G_RDA(Ab_, cur, 1, 1);
;             G_MMA(Aa, Bk1, 0); G_SB0();
;             asm volatile("s_waitcnt lgkmcnt(0)" ::: "memory");
;             WAIT_V0(); __syncthreads();
;         }
	v_mfma_f32_16x16x32_bf16 v[48:51], v[16:19], v[0:3], 0
	v_mfma_f32_16x16x32_bf16 v[52:55], v[20:23], v[0:3], 0
	v_mfma_f32_16x16x32_bf16 v[56:59], v[24:27], v[0:3], 0
	v_mfma_f32_16x16x32_bf16 v[60:63], v[28:31], v[0:3], 0
	v_mfma_f32_16x16x32_bf16 v[162:165], v[16:19], v[4:7], 0
	v_mfma_f32_16x16x32_bf16 v[166:169], v[20:23], v[4:7], 0
	v_mfma_f32_16x16x32_bf16 v[170:173], v[24:27], v[4:7], 0
	v_mfma_f32_16x16x32_bf16 v[174:177], v[28:31], v[4:7], 0
	v_mfma_f32_16x16x32_bf16 v[178:181], v[16:19], v[8:11], 0
	v_mfma_f32_16x16x32_bf16 v[182:185], v[20:23], v[8:11], 0
	v_mfma_f32_16x16x32_bf16 v[186:189], v[24:27], v[8:11], 0
	v_mfma_f32_16x16x32_bf16 v[204:207], v[28:31], v[8:11], 0
	v_mfma_f32_16x16x32_bf16 v[210:213], v[16:19], v[12:15], 0
	v_mfma_f32_16x16x32_bf16 v[214:217], v[20:23], v[12:15], 0
	v_mfma_f32_16x16x32_bf16 v[222:225], v[24:27], v[12:15], 0
	v_mfma_f32_16x16x32_bf16 v[226:229], v[28:31], v[12:15], 0
	s_setprio 0
	ds_read_b128 v[12:15], v218 offset:1024
	ds_read_b128 v[230:233], v218 offset:3072
	ds_read_b128 v[234:237], v218 offset:5120
	ds_read_b128 v[238:241], v218 offset:7168
	ds_read_b128 v[64:67], v219 offset:33792
	ds_read_b128 v[68:71], v219 offset:35840
	ds_read_b128 v[72:75], v219 offset:37888
	ds_read_b128 v[76:79], v219 offset:39936
	s_setprio 1
	v_mfma_f32_16x16x32_bf16 v[140:143], v[16:19], v[32:35], 0
	v_mfma_f32_16x16x32_bf16 v[136:139], v[20:23], v[32:35], 0
	v_mfma_f32_16x16x32_bf16 v[132:135], v[24:27], v[32:35], 0
	v_mfma_f32_16x16x32_bf16 v[128:131], v[28:31], v[32:35], 0
	v_mfma_f32_16x16x32_bf16 v[124:127], v[16:19], v[36:39], 0
	v_mfma_f32_16x16x32_bf16 v[120:123], v[20:23], v[36:39], 0
	v_mfma_f32_16x16x32_bf16 v[116:119], v[24:27], v[36:39], 0
	v_mfma_f32_16x16x32_bf16 v[112:115], v[28:31], v[36:39], 0
	v_mfma_f32_16x16x32_bf16 v[108:111], v[16:19], v[40:43], 0
	v_mfma_f32_16x16x32_bf16 v[104:107], v[20:23], v[40:43], 0
	v_mfma_f32_16x16x32_bf16 v[100:103], v[24:27], v[40:43], 0
	v_mfma_f32_16x16x32_bf16 v[96:99], v[28:31], v[40:43], 0
	v_mfma_f32_16x16x32_bf16 v[92:95], v[16:19], v[44:47], 0
	v_mfma_f32_16x16x32_bf16 v[88:91], v[20:23], v[44:47], 0
	v_mfma_f32_16x16x32_bf16 v[84:87], v[24:27], v[44:47], 0
	v_mfma_f32_16x16x32_bf16 v[80:83], v[28:31], v[44:47], 0
	s_setprio 0
	ds_read_b128 v[156:159], v218 offset:9216
	ds_read_b128 v[152:155], v218 offset:11264
	ds_read_b128 v[148:151], v218 offset:13312
	ds_read_b128 v[144:147], v218 offset:15360
	s_setprio 1
	s_waitcnt lgkmcnt(0)
	v_mfma_f32_16x16x32_bf16 v[0:3], v[64:67], v[12:15], v[48:51]
	v_mfma_f32_16x16x32_bf16 v[4:7], v[68:71], v[12:15], v[52:55]
	v_mfma_f32_16x16x32_bf16 v[8:11], v[72:75], v[12:15], v[56:59]
	v_mfma_f32_16x16x32_bf16 v[12:15], v[76:79], v[12:15], v[60:63]
	v_mfma_f32_16x16x32_bf16 v[16:19], v[64:67], v[230:233], v[162:165]
	v_mfma_f32_16x16x32_bf16 v[20:23], v[68:71], v[230:233], v[166:169]
	v_mfma_f32_16x16x32_bf16 v[24:27], v[72:75], v[230:233], v[170:173]
	v_mfma_f32_16x16x32_bf16 v[28:31], v[76:79], v[230:233], v[174:177]
	v_mfma_f32_16x16x32_bf16 v[32:35], v[64:67], v[234:237], v[178:181]
	v_mfma_f32_16x16x32_bf16 v[36:39], v[68:71], v[234:237], v[182:185]
	v_mfma_f32_16x16x32_bf16 v[40:43], v[72:75], v[234:237], v[186:189]
	v_mfma_f32_16x16x32_bf16 v[44:47], v[76:79], v[234:237], v[204:207]
	v_mfma_f32_16x16x32_bf16 v[48:51], v[64:67], v[238:241], v[210:213]
	v_mfma_f32_16x16x32_bf16 v[52:55], v[68:71], v[238:241], v[214:217]
	v_mfma_f32_16x16x32_bf16 v[56:59], v[72:75], v[238:241], v[222:225]
	v_mfma_f32_16x16x32_bf16 v[60:63], v[76:79], v[238:241], v[226:229]
	s_setprio 0
	v_lshlrev_b32_e32 v160, 8, v160
	v_lshlrev_b32_e32 v162, 4, v200
	v_lshlrev_b32_e32 v164, 4, v201
	v_lshlrev_b32_e32 v167, 4, v221
	v_and_or_b32 v160, v160, s90, v191
	v_lshlrev_b32_e32 v166, 11, v161
	s_add_u32 s6, s84, s46
	v_and_or_b32 v162, v162, s90, v191
	v_and_or_b32 v164, v164, s90, v191
	v_and_or_b32 v167, v167, s90, v191
	s_waitcnt lgkmcnt(0)
	v_or3_b32 v168, v160, v166, v190
	v_mov_b32_e32 v169, v193
	s_addc_u32 s7, s85, s47
	v_or3_b32 v170, v162, v166, v190
	v_mov_b32_e32 v171, v193
	v_or3_b32 v172, v164, v166, v190
	v_mov_b32_e32 v173, v193
	v_or3_b32 v174, v167, v166, v190
	v_mov_b32_e32 v175, v193
	s_waitcnt vmcnt(0)
	v_writelane_b32 v255, s52, 12
	v_writelane_b32 v255, s53, 13
	v_writelane_b32 v255, s64, 14
	v_writelane_b32 v255, s65, 15
	v_writelane_b32 v255, s30, 16
	s_mov_b64 s[64:65], s[6:7]
	s_add_u32 s6, s24, s50
	s_addc_u32 s7, s25, s51
	s_mov_b64 s[52:53], s[6:7]
	s_mov_b64 s[6:7], 0
	s_waitcnt vmcnt(0)
	v_lshrrev_b32_e32 v164, 6, v252
	v_lshlrev_b32_e32 v164, 10, v164
	s_nop 0
	v_readfirstlane_b32 s30, v164
	v_and_b32_e32 v165, 63, v252
	v_lshlrev_b32_e32 v165, 4, v165
	s_barrier
	s_and_b32 s43, s41, 0x10000
	v_add_u32_e32 v221, s43, v218
	v_or_b32_e32 v226, s43, v219
	s_xor_b32 s43, s43, 0x10000
	s_add_u32 s43, s43, s30
	.p2align	6

; #define LDSP __attribute__((address_space(3)))
; DI void attn_unit(const Params& p, int l, int b, int kvh, int qb, bool isctx, ldsp_t smem) {
;     int tid = threadIdx.x;
;     asm volatile("" : "+v"(tid));
;     const int wid = tid >> 6, lane = tid & 63, r = lane & 31, hh = lane >> 5;
;     const int head = kvh * 4 + (wid >> 1);
;     const int t0 = qb * 64 + (wid & 1) * 32;
;     const int nkeys = isctx ? CTXL : NKEY;
;     const bf16_t* Qp = isctx ? p.Qc + ((size_t)(b * 8 + head) * CTXL + t0) * 64 : p.Q + ((size_t)(b * 8 + head) * SEQ + t0) * 64;
;     const bf16_t* Kp = p.K + (size_t)(b * 2 + kvh) * NKEY * 64;
;     const bf16_t* Vp = p.Vt + (size_t)(b * 2 + kvh) * 64 * NKEY;
;     const int orow = isctx ? NLAT + b * CTXL + t0 : b * SEQ + t0;
;     bf16_t* Op = p.MIX + (size_t)orow * DM + head * 64;
;     const float cexp = p.smax[l] * LOG2E;
;     bf16x8 qf[4];
; #pragma unroll
;     for (int ks = 0; ks < 4; ++ks) qf[ks] = *(const bf16x8*)(Qp + (size_t)r * 64 + ks * 16 + 8 * hh);
;     f32x16 o[2];
; #pragma unroll
;     for (int i = 0; i < 16; ++i) { o[0][i] = 0.f; o[1][i] = 0.f; }
;     float rs0 = 0.f, rs1 = 0.f;
;     const int srow = tid >> 3, sch = tid & 7;
;     const int kdst = srow * 128 + ((sch ^ ((srow >> 1) & 7)) << 4);
;     const bf16_t* kg = Kp + (size_t)srow * 64 + sch * 8;
;     const bf16_t* vg = Vp + (size_t)srow * NKEY + sch * 8;
;     const int rsw = (r >> 1) & 7;
;     const int ntile = nkeys / 64;
;     ...
;     u32x4 kst, vst;
;     f32x16 sA[2], sB[2];
;     {
;         kst = *(const u32x4*)kg;
;         *(LDSP u32x4*)(smem + kdst) = kst;
;         kst = *(const u32x4*)(kg + (size_t)64 * 64);
;         vst = *(const u32x4*)vg;
;         __syncthreads();
;         ATT_QK(sA, smem);
;         *(LDSP u32x4*)(smem + 8192 + kdst) = kst;
;         *(LDSP u32x4*)(smem + 16384 + kdst) = vst;
;     }
.LBB0_163:
	v_mov_b32_e32 v24, v252
	s_lshl_b32 s9, s6, 2
	s_and_b32 s9, s9, 4
	v_ashrrev_i32_e32 v0, 7, v24
	v_add_u32_e32 v166, s9, v0
	s_lshl_b32 s9, s6, 3
	s_andn2_b32 s9, s9, 63
	v_lshrrev_b32_e32 v0, 1, v24
	v_and_or_b32 v144, v0, 32, s9
	s_and_b32 s9, s6, 7
	s_bfe_u32 s7, s6, 0x20001
	s_mul_i32 s98, s9, 0x88000
	v_ashrrev_i32_e32 v20, 3, v24
	s_add_u32 s10, s24, s98
	v_ashrrev_i32_e32 v21, 31, v20
	s_addc_u32 s11, s25, 0
	v_lshlrev_b32_e32 v10, 4, v24
	v_lshlrev_b64 v[0:1], 7, v[20:21]
	v_lshl_add_u64 v[0:1], s[10:11], 0, v[0:1]
	s_waitcnt lgkmcnt(5)
	v_and_b32_e32 v4, 0x70, v10
	s_waitcnt lgkmcnt(0)
	v_mov_b32_e32 v5, v193
	v_lshl_add_u64 v[146:147], v[0:1], 0, v[4:5]
	global_load_dwordx4 v[0:3], v[146:147], off
	global_load_dword v12, v193, s[4:5]
	v_lshl_add_u32 v6, s7, 3, v166
	v_ashrrev_i32_e32 v7, 31, v6
	v_ashrrev_i32_e32 v145, 31, v144
	v_lshlrev_b64 v[6:7], 19, v[6:7]
	v_and_b32_e32 v165, 31, v24
	v_lshlrev_b64 v[8:9], 7, v[144:145]
	v_lshl_add_u64 v[6:7], s[20:21], 0, v[6:7]
	v_bfe_u32 v164, v24, 5, 1
	v_lshl_add_u64 v[6:7], v[6:7], 0, v[8:9]
	v_lshlrev_b32_e32 v192, 7, v165
	v_lshl_add_u64 v[6:7], v[6:7], 0, v[192:193]
	v_lshlrev_b32_e32 v8, 4, v164
	v_mov_b32_e32 v9, v193
	v_lshl_add_u64 v[6:7], v[6:7], 0, v[8:9]
	global_load_dwordx4 v[112:115], v[6:7], off
	global_load_dwordx4 v[116:119], v[6:7], off offset:32
	global_load_dwordx4 v[120:123], v[6:7], off offset:64
	global_load_dwordx4 v[124:127], v[6:7], off offset:96
	v_lshrrev_b32_e32 v8, 5, v24
	v_bfe_u32 v16, v24, 1, 3
	s_add_u32 s10, s26, s98
	v_lshlrev_b32_e32 v9, 7, v20
	v_xor_b32_e32 v10, v10, v24
	v_bitop3_b32 v8, v8, v16, 1 bitop3:0x6c
	s_addc_u32 s11, s27, 0
	s_movk_i32 s9, 0x2000
	v_and_or_b32 v145, v10, s14, v9
	v_lshlrev_b32_e32 v167, 4, v8
	v_mov_b64_e32 v[8:9], s[10:11]
	s_movk_i32 s31, 0x2200
	v_add_co_u32_e32 v6, vcc, s9, v146
	v_mad_i64_i32 v[8:9], s[10:11], v20, s31, v[8:9]
	s_nop 0
	v_addc_co_u32_e32 v7, vcc, 0, v147, vcc
	v_lshl_add_u64 v[148:149], v[8:9], 0, v[4:5]
	global_load_dwordx4 v[4:7], v[6:7], off
	s_nop 0
	global_load_dwordx4 v[8:11], v[148:149], off
	v_or_b32_e32 v13, v192, v167
	v_mov_b64_e32 v[22:23], s[98:99]
	s_mov_b32 s9, -2
	s_movk_i32 s91, 0x2200
	s_waitcnt vmcnt(7)
	ds_write_b128 v145, v[0:3]
	s_waitcnt lgkmcnt(0)
	s_barrier
	ds_read_b128 v[0:3], v13
	s_waitcnt vmcnt(6)
	v_mul_f32_e32 v32, 0xbfb8aa3b, v12
	ds_read_b128 v[12:15], v13 offset:4096
	v_mov_b32_e32 v33, v32
	v_mov_b32_e32 v34, v32
	v_mov_b32_e32 v35, v32
	v_mov_b32_e32 v36, v32
	v_mov_b32_e32 v37, v32
	v_mov_b32_e32 v38, v32
	v_mov_b32_e32 v39, v32
	v_mov_b32_e32 v40, v32
	v_mov_b32_e32 v41, v32
	v_mov_b32_e32 v42, v32
	v_mov_b32_e32 v43, v32
	v_mov_b32_e32 v44, v32
	v_mov_b32_e32 v45, v32
	v_mov_b32_e32 v46, v32
	v_mov_b32_e32 v47, v32
	s_waitcnt vmcnt(5) lgkmcnt(1)
	s_nop 0
	v_mfma_f32_32x32x16_bf16 v[64:79], v[0:3], v[112:115], v[32:47]
	v_bitop3_b32 v0, v164, v16, 2 bitop3:0x36
	v_lshlrev_b32_e32 v168, 4, v0
	v_or_b32_e32 v17, v192, v168
	s_waitcnt lgkmcnt(0)
	v_mfma_f32_32x32x16_bf16 v[48:63], v[12:15], v[112:115], v[32:47]
	ds_read_b128 v[0:3], v17
	ds_read_b128 v[12:15], v17 offset:4096
	s_waitcnt vmcnt(4) lgkmcnt(1)
	v_mfma_f32_32x32x16_bf16 v[64:79], v[0:3], v[116:119], v[64:79]
	v_bitop3_b32 v0, v164, v16, 4 bitop3:0x36
	v_lshlrev_b32_e32 v169, 4, v0
	v_or_b32_e32 v17, v192, v169
	s_waitcnt lgkmcnt(0)
	v_mfma_f32_32x32x16_bf16 v[48:63], v[12:15], v[116:119], v[48:63]
	ds_read_b128 v[0:3], v17
	ds_read_b128 v[12:15], v17 offset:4096
	s_waitcnt vmcnt(3) lgkmcnt(1)
	v_mfma_f32_32x32x16_bf16 v[64:79], v[0:3], v[120:123], v[64:79]
	v_bitop3_b32 v0, v164, v16, 6 bitop3:0x36
	v_lshlrev_b32_e32 v170, 4, v0
	v_or_b32_e32 v21, v192, v170
	ds_read_b128 v[0:3], v21
	v_mov_b32_e32 v16, 0
	v_mov_b32_e32 v17, v16
	v_mov_b32_e32 v18, v16
	s_waitcnt lgkmcnt(1)
	v_mfma_f32_32x32x16_bf16 v[48:63], v[12:15], v[120:123], v[48:63]
	ds_read_b128 v[12:15], v21 offset:4096
	v_mov_b32_e32 v19, v16
	s_waitcnt vmcnt(1)
	ds_write_b128 v145, v[4:7] offset:8192
	s_waitcnt vmcnt(0)
	ds_write_b128 v145, v[8:11] offset:16384
	v_mov_b32_e32 v21, v16
	v_mov_b32_e32 v25, v16
	v_mov_b32_e32 v26, v16
	v_mov_b32_e32 v27, v16
	s_waitcnt lgkmcnt(3)
	v_mfma_f32_32x32x16_bf16 v[64:79], v[0:3], v[124:127], v[64:79]
	v_and_b32_e32 v2, 7, v24
	v_mad_i64_i32 v[0:1], s[10:11], v20, s31, v[22:23]
	v_lshl_or_b32 v0, v2, 4, v0
	v_lshl_add_u64 v[150:151], s[12:13], 0, v[0:1]
	v_mov_b32_e32 v20, v16
	v_mov_b32_e32 v22, v16
	s_waitcnt lgkmcnt(2)
	v_mfma_f32_32x32x16_bf16 v[48:63], v[12:15], v[124:127], v[48:63]
	v_mov_b32_e32 v23, v16
	v_mov_b32_e32 v24, v16
	v_mov_b32_e32 v28, v16
	v_mov_b32_e32 v29, v16
	v_mov_b32_e32 v30, v16
	v_mov_b32_e32 v31, v16
	v_mov_b32_e32 v0, v16
	v_mov_b32_e32 v1, v16
	v_mov_b32_e32 v2, v16
	v_mov_b32_e32 v3, v16
	v_mov_b32_e32 v4, v16
	v_mov_b32_e32 v5, v16
	v_mov_b32_e32 v6, v16
	v_mov_b32_e32 v7, v16
	v_mov_b32_e32 v8, v16
	v_mov_b32_e32 v9, v16
	v_mov_b32_e32 v10, v16
	v_mov_b32_e32 v11, v16
	v_mov_b32_e32 v12, v16
	v_mov_b32_e32 v13, v16
	v_mov_b32_e32 v14, v16
	v_mov_b32_e32 v15, v16
	v_mov_b32_e32 v136, v16
	v_mov_b32_e32 v137, v16
	.p2align	6

; #define WAIT_V0() asm volatile("s_waitcnt vmcnt(0)" ::: "memory")
; #define G_LANE_SETUP() \
;     int tid_ = threadIdx.x; \
;     asm volatile("" : "+v"(tid_));    \
;     const int wid = tid_ >> 6, lane = tid_ & 63, wr = wid >> 2, wc = wid & 3, fr = lane & 15, fq = lane >> 4; \
;     unsigned soff[4];        \
;     _Pragma("unroll") for (int i = 0; i < 4; ++i) { int sR, sC; stage_rc2(wid * 1024 + i * 8192 + lane * 16, sR, sC); soff[i] = (unsigned)(sR * K + sC) * 2u; }
; #define G_SB0() __builtin_amdgcn_sched_barrier(0)
; template <int EK>
; DI void gemm_stream(const Params& p, int l, const bf16_t* __restrict__ A, const bf16_t* __restrict__ Bt, int M, int N, int K, ldsp_t shm) {
;     ...
;     const int nt = K / 64;
;     int pm, pn;
;     tile_coords(L, nM, nN, pm, pn);
;     const bf16_t* Ab = A + (size_t)pm * 256 * K;
;     const bf16_t* Bb = Bt + (size_t)pn * 256 * K;
;     { G_LANE_SETUP(); (void)wr; (void)wc; (void)fr; (void)fq; G_STAGE(Ab, Bb, 0, 0); WAIT_V0(); __syncthreads(); }
;     while (true) {
;         G_LANE_SETUP();
;         const int aoff = lds_byte2(wr * 128 + fr, fq * 8), boff = lds_byte2(wc * 64 + fr, fq * 8);
;         f32x4 acc[8][4];
; #pragma unroll
;         for (int m = 0; m < 8; ++m)
; #pragma unroll
;             for (int n = 0; n < 4; ++n) acc[m][n] = (f32x4){0.f, 0.f, 0.f, 0.f};
;         const int Ln = L + gridDim.x;
;         const bool has_next = Ln < nwg;
;         int pm2 = pm, pn2 = pn;
;         if (has_next) tile_coords(Ln, nM, nN, pm2, pn2);
;         const bf16_t* Ab2 = A + (size_t)pm2 * 256 * K;
;         const bf16_t* Bb2 = Bt + (size_t)pn2 * 256 * K;
;         bf16x8 Aa[4], Ab_[4], Bk0[4], Bk1[4];
;     ...
;         for (int t = 0; t < nt; ++t) {
;             const int cur = t & 1;
;             G_RDA(Aa, cur, 0, 0); G_RDB(Bk0, cur, 0);
;             if (t + 1 < nt) G_STAGE_B(Bb, cur ^ 1, t + 1);
;             else if (has_next) G_STAGE_B(Bb2, cur ^ 1, 0);
;             G_SB0();
;             if (t > 0) G_MMA(Ab_, Bk1, 1);
;             G_SB0();
;             if (t + 1 < nt) G_STAGE_A(Ab, cur ^ 1, t + 1);
;             else if (has_next) G_STAGE_A(Ab2, cur ^ 1, 0);
;             G_RDA(Ab_, cur, 0, 1);
;             G_MMA(Aa, Bk0, 0); G_SB0();
;             G_RDA(Aa, cur, 1, 0); G_RDB(Bk1, cur, 1);
;             G_MMA(Ab_, Bk0, 1); G_SB0();
;             G_RDA(Ab_, cur, 1, 1);
;             G_MMA(Aa, Bk1, 0); G_SB0();
.LBB0_190:
	v_lshlrev_b32_e32 v0, 4, v160
	v_and_b32_e32 v1, 32, v160
	v_bfe_u32 v161, v160, 2, 4
	v_and_b32_e32 v190, 64, v160
	v_bitop3_b32 v191, v0, v1, 48 bitop3:0x6c
	v_lshrrev_b32_e32 v2, 3, v160
	v_or_b32_e32 v1, v191, v190
	v_and_or_b32 v2, v2, s15, v161
	v_add_u32_e32 v200, 0x2000, v0
	v_lshl_or_b32 v192, v2, 13, v1
	v_lshrrev_b32_e32 v2, 7, v200
	v_and_or_b32 v2, v2, s15, v161
	v_add_u32_e32 v201, 0x4000, v0
	v_add_u32_e32 v221, 0x6000, v0
	v_and_b32_e32 v220, 0xfffffc00, v0
	v_lshl_or_b32 v194, v2, 13, v1
	v_lshrrev_b32_e32 v2, 7, v201
	v_lshrrev_b32_e32 v0, 7, v221
	v_and_or_b32 v2, v2, s15, v161
	v_and_or_b32 v0, v0, s15, v161
	v_lshl_or_b32 v196, v2, 13, v1
	v_lshl_or_b32 v198, v0, 13, v1
	v_lshlrev_b32_e32 v1, 6, v160
	v_lshlrev_b32_e32 v4, 2, v160
	v_and_b32_e32 v0, 48, v160
	v_and_b32_e32 v2, 0x3c0, v1
	v_and_b32_e32 v4, 32, v4
	v_bitop3_b32 v0, v2, v4, v0 bitop3:0x36
	s_movk_i32 s4, 0xc000
	v_and_or_b32 v218, v1, s4, v0
	s_add_u32 s4, s9, s50
	s_addc_u32 s5, s31, s51
	v_add_u32_e32 v34, 0x18000, v220
	v_lshl_add_u64 v[32:33], s[4:5], 0, v[192:193]
	v_readfirstlane_b32 s43, v34
	v_lshlrev_b32_e32 v3, 7, v160
	v_lshl_add_u64 v[32:33], v[32:33], 0, s[0:1]
	s_mov_b32 m0, s43
	v_mov_b32_e32 v195, v193
	v_add_u32_e32 v34, 0x1a000, v220
	v_and_or_b32 v219, v3, s28, v0
	ds_read_b128 v[0:3], v218
	ds_read_b128 v[4:7], v218 offset:2048
	ds_read_b128 v[8:11], v218 offset:4096
	ds_read_b128 v[12:15], v218 offset:6144
	ds_read_b128 v[16:19], v219 offset:32768
	ds_read_b128 v[20:23], v219 offset:34816
	ds_read_b128 v[24:27], v219 offset:36864
	ds_read_b128 v[28:31], v219 offset:38912
	global_load_lds_dwordx4 v[32:33], off
	v_lshl_add_u64 v[32:33], s[4:5], 0, v[194:195]
	v_readfirstlane_b32 s43, v34
	v_lshl_add_u64 v[32:33], v[32:33], 0, s[0:1]
	s_mov_b32 m0, s43
	v_mov_b32_e32 v197, v193
	v_add_u32_e32 v34, 0x1c000, v220
	global_load_lds_dwordx4 v[32:33], off
	v_lshl_add_u64 v[32:33], s[4:5], 0, v[196:197]
	v_readfirstlane_b32 s43, v34
	v_lshl_add_u64 v[32:33], v[32:33], 0, s[0:1]
	s_mov_b32 m0, s43
	v_mov_b32_e32 v199, v193
	v_add_u32_e32 v34, 0x1e000, v220
	global_load_lds_dwordx4 v[32:33], off
	v_lshl_add_u64 v[32:33], s[4:5], 0, v[198:199]
	v_readfirstlane_b32 s4, v34
	v_lshl_add_u64 v[32:33], v[32:33], 0, s[0:1]
	s_mov_b32 m0, s4
	s_nop 0
	global_load_lds_dwordx4 v[32:33], off
	s_add_u32 s4, s12, s6
	s_addc_u32 s5, s13, s7
	v_add_u32_e32 v34, 0x10000, v220
	v_lshl_add_u64 v[32:33], s[4:5], 0, v[192:193]
	v_readfirstlane_b32 s43, v34
	v_lshl_add_u64 v[32:33], v[32:33], 0, s[0:1]
	s_mov_b32 m0, s43
	v_add_u32_e32 v34, 0x12000, v220
	global_load_lds_dwordx4 v[32:33], off
	v_lshl_add_u64 v[32:33], s[4:5], 0, v[194:195]
	v_readfirstlane_b32 s43, v34
	v_lshl_add_u64 v[32:33], v[32:33], 0, s[0:1]
	s_mov_b32 m0, s43
	v_add_u32_e32 v34, 0x14000, v220
	global_load_lds_dwordx4 v[32:33], off
	v_lshl_add_u64 v[32:33], s[4:5], 0, v[196:197]
	v_readfirstlane_b32 s43, v34
	v_lshl_add_u64 v[32:33], v[32:33], 0, s[0:1]
	s_mov_b32 m0, s43
	v_add_u32_e32 v34, 0x16000, v220
	global_load_lds_dwordx4 v[32:33], off
	v_lshl_add_u64 v[32:33], s[4:5], 0, v[198:199]
	v_readfirstlane_b32 s4, v34
	v_lshl_add_u64 v[32:33], v[32:33], 0, s[0:1]
	s_mov_b32 m0, s4
	s_mov_b32 s43, 0x10000
	global_load_lds_dwordx4 v[32:33], off
	ds_read_b128 v[32:35], v218 offset:8192
	ds_read_b128 v[36:39], v218 offset:10240
	ds_read_b128 v[40:43], v218 offset:12288
	ds_read_b128 v[44:47], v218 offset:14336
	s_setprio 1
	s_waitcnt lgkmcnt(0)
; #define WAIT_V0() asm volatile("s_waitcnt vmcnt(0)" ::: "memory")
; #define G_STAGE_A(Ap, buf, kt) do { const char* ab_ = (const char*)(Ap) + (size_t)(kt) * 128; \
;       _Pragma("unroll") for (int i = 0; i < 4; ++i) \
;         __builtin_amdgcn_global_load_lds((const unsigned*)(ab_ + soff[i]), (LDSP unsigned*)(G_SA(buf) + wid * 1024 + i * 8192), 16, 0, 0); } while (0)
; #define G_STAGE_B(Bp, buf, kt) do { const char* bb_ = (const char*)(Bp) + (size_t)(kt) * 128; \
;       _Pragma("unroll") for (int i = 0; i < 4; ++i) \
;         __builtin_amdgcn_global_load_lds((const unsigned*)(bb_ + soff[i]), (LDSP unsigned*)(G_SB(buf) + wid * 1024 + i * 8192), 16, 0, 0); } while (0)
; #define G_RDA(AF, buf, ks, mh) do { _Pragma("unroll") for (int m = 0; m < 4; ++m) AF[m] = *(const LDSP bf16x8*)(G_SA(buf) + aoff + ((mh) * 4 + m) * 2048 + (ks) * 1024); } while (0)
; #define G_RDB(BF, buf, ks) do { _Pragma("unroll") for (int n = 0; n < 4; ++n) BF[n] = *(const LDSP bf16x8*)(G_SB(buf) + boff + n * 2048 + (ks) * 1024); } while (0)
; #define G_MMA(AF, BF, mh) do { __builtin_amdgcn_s_setprio(1); \
;             _Pragma("unroll") for (int m = 0; m < 4; ++m) _Pragma("unroll") for (int n = 0; n < 4; ++n) \
;                 acc[(mh) * 4 + m][n] = __builtin_amdgcn_mfma_f32_16x16x32_bf16(BF[n], AF[m], acc[(mh) * 4 + m][n], 0, 0, 0); \
;             __builtin_amdgcn_s_setprio(0); } while (0)
; template <int EK>
; DI void gemm_stream(const Params& p, int l, const bf16_t* __restrict__ A, const bf16_t* __restrict__ Bt, int M, int N, int K, ldsp_t shm) {
;     ...
;         for (int t = 0; t < nt; ++t) {
;             const int cur = t & 1;
;             G_RDA(Aa, cur, 0, 0); G_RDB(Bk0, cur, 0);
;             if (t + 1 < nt) G_STAGE_B(Bb, cur ^ 1, t + 1);
;             else if (has_next) G_STAGE_B(Bb2, cur ^ 1, 0);
;             G_SB0();
;             if (t > 0) G_MMA(Ab_, Bk1, 1);
;             G_SB0();
;             if (t + 1 < nt) G_STAGE_A(Ab, cur ^ 1, t + 1);
;             else if (has_next) G_STAGE_A(Ab2, cur ^ 1, 0);
;             G_RDA(Ab_, cur, 0, 1);
;             G_MMA(Aa, Bk0, 0); G_SB0();
;             G_RDA(Aa, cur, 1, 0); G_RDB(Bk1, cur, 1);
;             G_MMA(Ab_, Bk0, 1); G_SB0();
;             G_RDA(Ab_, cur, 1, 1);
;             G_MMA(Aa, Bk1, 0); G_SB0();
;             asm volatile("s_waitcnt lgkmcnt(0)" ::: "memory");
;             WAIT_V0(); __syncthreads();
;         }
	v_mfma_f32_16x16x32_bf16 v[48:51], v[16:19], v[0:3], 0
	v_mfma_f32_16x16x32_bf16 v[52:55], v[20:23], v[0:3], 0
	v_mfma_f32_16x16x32_bf16 v[56:59], v[24:27], v[0:3], 0
	v_mfma_f32_16x16x32_bf16 v[60:63], v[28:31], v[0:3], 0
	v_mfma_f32_16x16x32_bf16 v[162:165], v[16:19], v[4:7], 0
	v_mfma_f32_16x16x32_bf16 v[166:169], v[20:23], v[4:7], 0
	v_mfma_f32_16x16x32_bf16 v[170:173], v[24:27], v[4:7], 0
	v_mfma_f32_16x16x32_bf16 v[174:177], v[28:31], v[4:7], 0
	v_mfma_f32_16x16x32_bf16 v[178:181], v[16:19], v[8:11], 0
	v_mfma_f32_16x16x32_bf16 v[182:185], v[20:23], v[8:11], 0
	v_mfma_f32_16x16x32_bf16 v[186:189], v[24:27], v[8:11], 0
	v_mfma_f32_16x16x32_bf16 v[204:207], v[28:31], v[8:11], 0
	v_mfma_f32_16x16x32_bf16 v[210:213], v[16:19], v[12:15], 0
	v_mfma_f32_16x16x32_bf16 v[214:217], v[20:23], v[12:15], 0
	v_mfma_f32_16x16x32_bf16 v[222:225], v[24:27], v[12:15], 0
	v_mfma_f32_16x16x32_bf16 v[226:229], v[28:31], v[12:15], 0
	s_setprio 0
	ds_read_b128 v[12:15], v218 offset:1024
	ds_read_b128 v[230:233], v218 offset:3072
	ds_read_b128 v[234:237], v218 offset:5120
	ds_read_b128 v[238:241], v218 offset:7168
	ds_read_b128 v[64:67], v219 offset:33792
	ds_read_b128 v[68:71], v219 offset:35840
	ds_read_b128 v[72:75], v219 offset:37888
	ds_read_b128 v[76:79], v219 offset:39936
	s_setprio 1
	v_mfma_f32_16x16x32_bf16 v[140:143], v[16:19], v[32:35], 0
	v_mfma_f32_16x16x32_bf16 v[136:139], v[20:23], v[32:35], 0
	v_mfma_f32_16x16x32_bf16 v[132:135], v[24:27], v[32:35], 0
	v_mfma_f32_16x16x32_bf16 v[128:131], v[28:31], v[32:35], 0
	v_mfma_f32_16x16x32_bf16 v[124:127], v[16:19], v[36:39], 0
	v_mfma_f32_16x16x32_bf16 v[120:123], v[20:23], v[36:39], 0
	v_mfma_f32_16x16x32_bf16 v[116:119], v[24:27], v[36:39], 0
	v_mfma_f32_16x16x32_bf16 v[112:115], v[28:31], v[36:39], 0
	v_mfma_f32_16x16x32_bf16 v[108:111], v[16:19], v[40:43], 0
	v_mfma_f32_16x16x32_bf16 v[104:107], v[20:23], v[40:43], 0
	v_mfma_f32_16x16x32_bf16 v[100:103], v[24:27], v[40:43], 0
	v_mfma_f32_16x16x32_bf16 v[96:99], v[28:31], v[40:43], 0
	v_mfma_f32_16x16x32_bf16 v[92:95], v[16:19], v[44:47], 0
	v_mfma_f32_16x16x32_bf16 v[88:91], v[20:23], v[44:47], 0
	v_mfma_f32_16x16x32_bf16 v[84:87], v[24:27], v[44:47], 0
	v_mfma_f32_16x16x32_bf16 v[80:83], v[28:31], v[44:47], 0
	s_setprio 0
	ds_read_b128 v[156:159], v218 offset:9216
	ds_read_b128 v[152:155], v218 offset:11264
	ds_read_b128 v[148:151], v218 offset:13312
	ds_read_b128 v[144:147], v218 offset:15360
	s_setprio 1
	s_waitcnt lgkmcnt(0)
	v_mfma_f32_16x16x32_bf16 v[0:3], v[64:67], v[12:15], v[48:51]
	v_mfma_f32_16x16x32_bf16 v[4:7], v[68:71], v[12:15], v[52:55]
	v_mfma_f32_16x16x32_bf16 v[8:11], v[72:75], v[12:15], v[56:59]
	v_mfma_f32_16x16x32_bf16 v[12:15], v[76:79], v[12:15], v[60:63]
	v_mfma_f32_16x16x32_bf16 v[16:19], v[64:67], v[230:233], v[162:165]
	v_mfma_f32_16x16x32_bf16 v[20:23], v[68:71], v[230:233], v[166:169]
	v_mfma_f32_16x16x32_bf16 v[24:27], v[72:75], v[230:233], v[170:173]
	v_mfma_f32_16x16x32_bf16 v[28:31], v[76:79], v[230:233], v[174:177]
	v_mfma_f32_16x16x32_bf16 v[32:35], v[64:67], v[234:237], v[178:181]
	v_mfma_f32_16x16x32_bf16 v[36:39], v[68:71], v[234:237], v[182:185]
	v_mfma_f32_16x16x32_bf16 v[40:43], v[72:75], v[234:237], v[186:189]
	v_mfma_f32_16x16x32_bf16 v[44:47], v[76:79], v[234:237], v[204:207]
	v_mfma_f32_16x16x32_bf16 v[48:51], v[64:67], v[238:241], v[210:213]
	v_mfma_f32_16x16x32_bf16 v[52:55], v[68:71], v[238:241], v[214:217]
	v_mfma_f32_16x16x32_bf16 v[56:59], v[72:75], v[238:241], v[222:225]
	v_mfma_f32_16x16x32_bf16 v[60:63], v[76:79], v[238:241], v[226:229]
	s_setprio 0
	v_lshlrev_b32_e32 v160, 10, v160
	s_mov_b32 s47, 0xfffe0000
	v_lshlrev_b32_e32 v162, 6, v200
	v_lshlrev_b32_e32 v164, 6, v201
	v_lshlrev_b32_e32 v167, 6, v221
	v_and_or_b32 v160, v160, s47, v191
	v_lshlrev_b32_e32 v166, 13, v161
	s_add_u32 s4, s84, s50
	v_and_or_b32 v162, v162, s47, v191
	v_and_or_b32 v164, v164, s47, v191
	v_and_or_b32 v167, v167, s47, v191
	s_waitcnt lgkmcnt(0)
	v_or3_b32 v168, v160, v166, v190
	v_mov_b32_e32 v169, v193
	s_addc_u32 s5, s85, s51
	v_or3_b32 v170, v162, v166, v190
	v_mov_b32_e32 v171, v193
	v_or3_b32 v172, v164, v166, v190
	v_mov_b32_e32 v173, v193
	v_or3_b32 v174, v167, v166, v190
	v_mov_b32_e32 v175, v193
	s_waitcnt vmcnt(0)
	v_writelane_b32 v255, s52, 12
	v_writelane_b32 v255, s53, 13
	v_writelane_b32 v255, s64, 14
	v_writelane_b32 v255, s65, 15
	v_writelane_b32 v255, s30, 16
	s_mov_b64 s[64:65], s[4:5]
	s_add_u32 s4, s8, s6
	s_addc_u32 s5, s14, s7
	s_mov_b64 s[52:53], s[4:5]
	s_mov_b64 s[4:5], 0
	s_waitcnt vmcnt(0)
	v_lshrrev_b32_e32 v164, 6, v252
	v_lshlrev_b32_e32 v164, 10, v164
	s_nop 0
	v_readfirstlane_b32 s30, v164
	v_and_b32_e32 v165, 63, v252
	v_lshlrev_b32_e32 v165, 4, v165
	s_barrier
	s_and_b32 s6, s43, 0x10000
	v_add_u32_e32 v221, s6, v218
	v_or_b32_e32 v226, s6, v219
	s_xor_b32 s6, s6, 0x10000
	s_add_u32 s6, s6, s30
	.p2align	6

; #define WAIT_V0() asm volatile("s_waitcnt vmcnt(0)" ::: "memory")
; #define G_LANE_SETUP() \
;     int tid_ = threadIdx.x; \
;     asm volatile("" : "+v"(tid_));    \
;     const int wid = tid_ >> 6, lane = tid_ & 63, wr = wid >> 2, wc = wid & 3, fr = lane & 15, fq = lane >> 4; \
;     unsigned soff[4];        \
;     _Pragma("unroll") for (int i = 0; i < 4; ++i) { int sR, sC; stage_rc2(wid * 1024 + i * 8192 + lane * 16, sR, sC); soff[i] = (unsigned)(sR * K + sC) * 2u; }
; #define G_SB0() __builtin_amdgcn_sched_barrier(0)
; template <int EK>
; DI void gemm_stream(const Params& p, int l, const bf16_t* __restrict__ A, const bf16_t* __restrict__ Bt, int M, int N, int K, ldsp_t shm) {
;     ...
;     const int nt = K / 64;
;     int pm, pn;
;     tile_coords(L, nM, nN, pm, pn);
;     const bf16_t* Ab = A + (size_t)pm * 256 * K;
;     const bf16_t* Bb = Bt + (size_t)pn * 256 * K;
;     { G_LANE_SETUP(); (void)wr; (void)wc; (void)fr; (void)fq; G_STAGE(Ab, Bb, 0, 0); WAIT_V0(); __syncthreads(); }
;     while (true) {
;         G_LANE_SETUP();
;         const int aoff = lds_byte2(wr * 128 + fr, fq * 8), boff = lds_byte2(wc * 64 + fr, fq * 8);
;         f32x4 acc[8][4];
; #pragma unroll
;         for (int m = 0; m < 8; ++m)
; #pragma unroll
;             for (int n = 0; n < 4; ++n) acc[m][n] = (f32x4){0.f, 0.f, 0.f, 0.f};
;         const int Ln = L + gridDim.x;
;         const bool has_next = Ln < nwg;
;         int pm2 = pm, pn2 = pn;
;         if (has_next) tile_coords(Ln, nM, nN, pm2, pn2);
;         const bf16_t* Ab2 = A + (size_t)pm2 * 256 * K;
;         const bf16_t* Bb2 = Bt + (size_t)pn2 * 256 * K;
;         bf16x8 Aa[4], Ab_[4], Bk0[4], Bk1[4];
;     ...
;         for (int t = 0; t < nt; ++t) {
;             const int cur = t & 1;
;             G_RDA(Aa, cur, 0, 0); G_RDB(Bk0, cur, 0);
;             if (t + 1 < nt) G_STAGE_B(Bb, cur ^ 1, t + 1);
;             else if (has_next) G_STAGE_B(Bb2, cur ^ 1, 0);
;             G_SB0();
;             if (t > 0) G_MMA(Ab_, Bk1, 1);
;             G_SB0();
;             if (t + 1 < nt) G_STAGE_A(Ab, cur ^ 1, t + 1);
;             else if (has_next) G_STAGE_A(Ab2, cur ^ 1, 0);
;             G_RDA(Ab_, cur, 0, 1);
;             G_MMA(Aa, Bk0, 0); G_SB0();
;             G_RDA(Aa, cur, 1, 0); G_RDB(Bk1, cur, 1);
;             G_MMA(Ab_, Bk0, 1); G_SB0();
;             G_RDA(Ab_, cur, 1, 1);
;             G_MMA(Aa, Bk1, 0); G_SB0();
.LBB0_263:
	v_lshlrev_b32_e32 v0, 4, v160
	v_and_b32_e32 v1, 32, v160
	v_bfe_u32 v161, v160, 2, 4
	v_and_b32_e32 v190, 64, v160
	v_bitop3_b32 v191, v0, v1, 48 bitop3:0x6c
	v_lshrrev_b32_e32 v2, 3, v160
	v_or_b32_e32 v1, v191, v190
	v_and_or_b32 v2, v2, s86, v161
	v_add_u32_e32 v200, 0x2000, v0
	v_lshl_or_b32 v192, v2, 11, v1
	v_lshrrev_b32_e32 v2, 7, v200
	v_and_or_b32 v2, v2, s86, v161
	v_add_u32_e32 v201, 0x4000, v0
	v_add_u32_e32 v204, 0x6000, v0
	v_and_b32_e32 v220, 0xfffffc00, v0
	v_lshl_or_b32 v194, v2, 11, v1
	v_lshrrev_b32_e32 v2, 7, v201
	v_lshrrev_b32_e32 v0, 7, v204
	v_and_or_b32 v2, v2, s86, v161
	v_and_or_b32 v0, v0, s86, v161
	v_lshl_or_b32 v196, v2, 11, v1
	v_lshl_or_b32 v198, v0, 11, v1
	v_lshlrev_b32_e32 v1, 6, v160
	v_lshlrev_b32_e32 v4, 2, v160
	v_and_b32_e32 v0, 48, v160
	v_and_b32_e32 v2, 0x3c0, v1
	v_and_b32_e32 v4, 32, v4
	v_bitop3_b32 v0, v2, v4, v0 bitop3:0x36
	s_movk_i32 s4, 0xc000
	v_and_or_b32 v218, v1, s4, v0
	s_add_u32 s4, s14, s46
	s_addc_u32 s5, s15, s47
	v_add_u32_e32 v34, 0x18000, v220
	v_lshl_add_u64 v[32:33], s[4:5], 0, v[192:193]
	v_readfirstlane_b32 s8, v34
	v_lshlrev_b32_e32 v3, 7, v160
	v_lshl_add_u64 v[32:33], v[32:33], 0, s[0:1]
	s_mov_b32 m0, s8
	v_mov_b32_e32 v195, v193
	v_add_u32_e32 v34, 0x1a000, v220
	v_and_or_b32 v219, v3, s28, v0
	ds_read_b128 v[0:3], v218
	ds_read_b128 v[4:7], v218 offset:2048
	ds_read_b128 v[8:11], v218 offset:4096
	ds_read_b128 v[12:15], v218 offset:6144
	ds_read_b128 v[16:19], v219 offset:32768
	ds_read_b128 v[20:23], v219 offset:34816
	ds_read_b128 v[24:27], v219 offset:36864
	ds_read_b128 v[28:31], v219 offset:38912
	global_load_lds_dwordx4 v[32:33], off
	v_lshl_add_u64 v[32:33], s[4:5], 0, v[194:195]
	v_readfirstlane_b32 s8, v34
	v_lshl_add_u64 v[32:33], v[32:33], 0, s[0:1]
	s_mov_b32 m0, s8
	v_mov_b32_e32 v197, v193
	v_add_u32_e32 v34, 0x1c000, v220
	global_load_lds_dwordx4 v[32:33], off
	v_lshl_add_u64 v[32:33], s[4:5], 0, v[196:197]
	v_readfirstlane_b32 s8, v34
	v_lshl_add_u64 v[32:33], v[32:33], 0, s[0:1]
	s_mov_b32 m0, s8
	v_mov_b32_e32 v199, v193
	v_add_u32_e32 v34, 0x1e000, v220
	global_load_lds_dwordx4 v[32:33], off
	v_lshl_add_u64 v[32:33], s[4:5], 0, v[198:199]
	v_readfirstlane_b32 s4, v34
	v_lshl_add_u64 v[32:33], v[32:33], 0, s[0:1]
	s_mov_b32 m0, s4
	s_nop 0
	global_load_lds_dwordx4 v[32:33], off
	s_add_u32 s4, s82, s36
	s_addc_u32 s5, s83, s37
	v_add_u32_e32 v34, 0x10000, v220
	v_lshl_add_u64 v[32:33], s[4:5], 0, v[192:193]
	v_readfirstlane_b32 s8, v34
	v_lshl_add_u64 v[32:33], v[32:33], 0, s[0:1]
	s_mov_b32 m0, s8
	v_add_u32_e32 v34, 0x12000, v220
	global_load_lds_dwordx4 v[32:33], off
	v_lshl_add_u64 v[32:33], s[4:5], 0, v[194:195]
	v_readfirstlane_b32 s8, v34
	v_lshl_add_u64 v[32:33], v[32:33], 0, s[0:1]
	s_mov_b32 m0, s8
	v_add_u32_e32 v34, 0x14000, v220
	global_load_lds_dwordx4 v[32:33], off
	v_lshl_add_u64 v[32:33], s[4:5], 0, v[196:197]
	v_readfirstlane_b32 s8, v34
	v_lshl_add_u64 v[32:33], v[32:33], 0, s[0:1]
	s_mov_b32 m0, s8
	v_add_u32_e32 v34, 0x16000, v220
	global_load_lds_dwordx4 v[32:33], off
	v_lshl_add_u64 v[32:33], s[4:5], 0, v[198:199]
	v_readfirstlane_b32 s4, v34
	v_lshl_add_u64 v[32:33], v[32:33], 0, s[0:1]
	s_mov_b32 m0, s4
	s_mov_b32 s8, 0x10000
	global_load_lds_dwordx4 v[32:33], off
	ds_read_b128 v[32:35], v218 offset:8192
	ds_read_b128 v[36:39], v218 offset:10240
	ds_read_b128 v[40:43], v218 offset:12288
	ds_read_b128 v[44:47], v218 offset:14336
	s_setprio 1
	s_waitcnt lgkmcnt(0)
; #define WAIT_V0() asm volatile("s_waitcnt vmcnt(0)" ::: "memory")
; #define G_STAGE_A(Ap, buf, kt) do { const char* ab_ = (const char*)(Ap) + (size_t)(kt) * 128; \
;       _Pragma("unroll") for (int i = 0; i < 4; ++i) \
;         __builtin_amdgcn_global_load_lds((const unsigned*)(ab_ + soff[i]), (LDSP unsigned*)(G_SA(buf) + wid * 1024 + i * 8192), 16, 0, 0); } while (0)
; #define G_STAGE_B(Bp, buf, kt) do { const char* bb_ = (const char*)(Bp) + (size_t)(kt) * 128; \
;       _Pragma("unroll") for (int i = 0; i < 4; ++i) \
;         __builtin_amdgcn_global_load_lds((const unsigned*)(bb_ + soff[i]), (LDSP unsigned*)(G_SB(buf) + wid * 1024 + i * 8192), 16, 0, 0); } while (0)
; #define G_RDA(AF, buf, ks, mh) do { _Pragma("unroll") for (int m = 0; m < 4; ++m) AF[m] = *(const LDSP bf16x8*)(G_SA(buf) + aoff + ((mh) * 4 + m) * 2048 + (ks) * 1024); } while (0)
; #define G_RDB(BF, buf, ks) do { _Pragma("unroll") for (int n = 0; n < 4; ++n) BF[n] = *(const LDSP bf16x8*)(G_SB(buf) + boff + n * 2048 + (ks) * 1024); } while (0)
; #define G_MMA(AF, BF, mh) do { __builtin_amdgcn_s_setprio(1); \
;             _Pragma("unroll") for (int m = 0; m < 4; ++m) _Pragma("unroll") for (int n = 0; n < 4; ++n) \
;                 acc[(mh) * 4 + m][n] = __builtin_amdgcn_mfma_f32_16x16x32_bf16(BF[n], AF[m], acc[(mh) * 4 + m][n], 0, 0, 0); \
;             __builtin_amdgcn_s_setprio(0); } while (0)
; template <int EK>
; DI void gemm_stream(const Params& p, int l, const bf16_t* __restrict__ A, const bf16_t* __restrict__ Bt, int M, int N, int K, ldsp_t shm) {
;     ...
;         for (int t = 0; t < nt; ++t) {
;             const int cur = t & 1;
;             G_RDA(Aa, cur, 0, 0); G_RDB(Bk0, cur, 0);
;             if (t + 1 < nt) G_STAGE_B(Bb, cur ^ 1, t + 1);
;             else if (has_next) G_STAGE_B(Bb2, cur ^ 1, 0);
;             G_SB0();
;             if (t > 0) G_MMA(Ab_, Bk1, 1);
;             G_SB0();
;             if (t + 1 < nt) G_STAGE_A(Ab, cur ^ 1, t + 1);
;             else if (has_next) G_STAGE_A(Ab2, cur ^ 1, 0);
;             G_RDA(Ab_, cur, 0, 1);
;             G_MMA(Aa, Bk0, 0); G_SB0();
;             G_RDA(Aa, cur, 1, 0); G_RDB(Bk1, cur, 1);
;             G_MMA(Ab_, Bk0, 1); G_SB0();
;             G_RDA(Ab_, cur, 1, 1);
;             G_MMA(Aa, Bk1, 0); G_SB0();
;             asm volatile("s_waitcnt lgkmcnt(0)" ::: "memory");
;             WAIT_V0(); __syncthreads();
	v_mfma_f32_16x16x32_bf16 v[48:51], v[16:19], v[0:3], 0
	v_mfma_f32_16x16x32_bf16 v[52:55], v[20:23], v[0:3], 0
	v_mfma_f32_16x16x32_bf16 v[56:59], v[24:27], v[0:3], 0
	v_mfma_f32_16x16x32_bf16 v[60:63], v[28:31], v[0:3], 0
	v_mfma_f32_16x16x32_bf16 v[162:165], v[16:19], v[4:7], 0
	v_mfma_f32_16x16x32_bf16 v[166:169], v[20:23], v[4:7], 0
	v_mfma_f32_16x16x32_bf16 v[170:173], v[24:27], v[4:7], 0
	v_mfma_f32_16x16x32_bf16 v[174:177], v[28:31], v[4:7], 0
	v_mfma_f32_16x16x32_bf16 v[178:181], v[16:19], v[8:11], 0
	v_mfma_f32_16x16x32_bf16 v[182:185], v[20:23], v[8:11], 0
	v_mfma_f32_16x16x32_bf16 v[186:189], v[24:27], v[8:11], 0
	v_mfma_f32_16x16x32_bf16 v[222:225], v[28:31], v[8:11], 0
	v_mfma_f32_16x16x32_bf16 v[226:229], v[16:19], v[12:15], 0
	v_mfma_f32_16x16x32_bf16 v[230:233], v[20:23], v[12:15], 0
	v_mfma_f32_16x16x32_bf16 v[234:237], v[24:27], v[12:15], 0
	v_mfma_f32_16x16x32_bf16 v[238:241], v[28:31], v[12:15], 0
	s_setprio 0
	ds_read_b128 v[12:15], v218 offset:1024
	ds_read_b128 v[242:245], v218 offset:3072
	ds_read_b128 v[246:249], v218 offset:5120
	ds_read_b128 v[214:217], v218 offset:7168
	ds_read_b128 v[64:67], v219 offset:33792
	ds_read_b128 v[68:71], v219 offset:35840
	ds_read_b128 v[76:79], v219 offset:37888
	ds_read_b128 v[72:75], v219 offset:39936
	s_setprio 1
	v_mfma_f32_16x16x32_bf16 v[128:131], v[16:19], v[32:35], 0
	v_mfma_f32_16x16x32_bf16 v[124:127], v[20:23], v[32:35], 0
	v_mfma_f32_16x16x32_bf16 v[120:123], v[24:27], v[32:35], 0
	v_mfma_f32_16x16x32_bf16 v[116:119], v[28:31], v[32:35], 0
	v_mfma_f32_16x16x32_bf16 v[112:115], v[16:19], v[36:39], 0
	v_mfma_f32_16x16x32_bf16 v[108:111], v[20:23], v[36:39], 0
	v_mfma_f32_16x16x32_bf16 v[104:107], v[24:27], v[36:39], 0
	v_mfma_f32_16x16x32_bf16 v[100:103], v[28:31], v[36:39], 0
	v_mfma_f32_16x16x32_bf16 v[96:99], v[16:19], v[40:43], 0
	v_mfma_f32_16x16x32_bf16 v[92:95], v[20:23], v[40:43], 0
	v_mfma_f32_16x16x32_bf16 v[88:91], v[24:27], v[40:43], 0
	v_mfma_f32_16x16x32_bf16 v[84:87], v[28:31], v[40:43], 0
	v_mfma_f32_16x16x32_bf16 v[132:135], v[16:19], v[44:47], 0
	v_mfma_f32_16x16x32_bf16 v[136:139], v[20:23], v[44:47], 0
	v_mfma_f32_16x16x32_bf16 v[140:143], v[24:27], v[44:47], 0
	v_mfma_f32_16x16x32_bf16 v[80:83], v[28:31], v[44:47], 0
	s_setprio 0
	ds_read_b128 v[156:159], v218 offset:9216
	ds_read_b128 v[152:155], v218 offset:11264
	ds_read_b128 v[148:151], v218 offset:13312
	ds_read_b128 v[144:147], v218 offset:15360
	s_setprio 1
	s_waitcnt lgkmcnt(0)
	v_mfma_f32_16x16x32_bf16 v[0:3], v[64:67], v[12:15], v[48:51]
	v_mfma_f32_16x16x32_bf16 v[4:7], v[68:71], v[12:15], v[52:55]
	v_mfma_f32_16x16x32_bf16 v[8:11], v[76:79], v[12:15], v[56:59]
	v_mfma_f32_16x16x32_bf16 v[12:15], v[72:75], v[12:15], v[60:63]
	v_mfma_f32_16x16x32_bf16 v[16:19], v[64:67], v[242:245], v[162:165]
	v_mfma_f32_16x16x32_bf16 v[20:23], v[68:71], v[242:245], v[166:169]
	v_mfma_f32_16x16x32_bf16 v[24:27], v[76:79], v[242:245], v[170:173]
	v_mfma_f32_16x16x32_bf16 v[28:31], v[72:75], v[242:245], v[174:177]
	v_mfma_f32_16x16x32_bf16 v[32:35], v[64:67], v[246:249], v[178:181]
	v_mfma_f32_16x16x32_bf16 v[36:39], v[68:71], v[246:249], v[182:185]
	v_mfma_f32_16x16x32_bf16 v[40:43], v[76:79], v[246:249], v[186:189]
	v_mfma_f32_16x16x32_bf16 v[44:47], v[72:75], v[246:249], v[222:225]
	v_mfma_f32_16x16x32_bf16 v[48:51], v[64:67], v[214:217], v[226:229]
	v_mfma_f32_16x16x32_bf16 v[52:55], v[68:71], v[214:217], v[230:233]
	v_mfma_f32_16x16x32_bf16 v[56:59], v[76:79], v[214:217], v[234:237]
	v_mfma_f32_16x16x32_bf16 v[60:63], v[72:75], v[214:217], v[238:241]
	s_setprio 0
	v_lshlrev_b32_e32 v160, 8, v160
	s_movk_i32 s9, 0x8000
	v_readlane_b32 s4, v255, 10
	v_lshlrev_b32_e32 v162, 4, v200
	v_lshlrev_b32_e32 v164, 4, v201
	v_lshlrev_b32_e32 v167, 4, v204
	v_and_or_b32 v160, v160, s9, v191
	v_lshlrev_b32_e32 v166, 11, v161
	s_add_u32 s4, s4, s46
	v_readlane_b32 s5, v255, 7
	v_and_or_b32 v162, v162, s9, v191
	v_and_or_b32 v164, v164, s9, v191
	v_and_or_b32 v167, v167, s9, v191
	s_waitcnt lgkmcnt(0)
	v_or3_b32 v168, v160, v166, v190
	v_mov_b32_e32 v169, v193
	s_addc_u32 s5, s5, s47
	v_or3_b32 v170, v162, v166, v190
	v_mov_b32_e32 v171, v193
	v_or3_b32 v172, v164, v166, v190
	v_mov_b32_e32 v173, v193
	v_or3_b32 v174, v167, v166, v190
	v_mov_b32_e32 v175, v193
	s_waitcnt vmcnt(0)
	v_writelane_b32 v255, s52, 12
	v_writelane_b32 v255, s53, 13
	v_writelane_b32 v255, s64, 14
	v_writelane_b32 v255, s65, 15
	v_writelane_b32 v255, s30, 16
	s_mov_b64 s[64:65], s[4:5]
	s_add_u32 s4, s38, s36
	s_addc_u32 s5, s39, s37
	s_mov_b64 s[52:53], s[4:5]
	s_mov_b64 s[4:5], 0
	s_waitcnt vmcnt(0)
	v_lshrrev_b32_e32 v164, 6, v252
	v_lshlrev_b32_e32 v164, 10, v164
	s_nop 0
	v_readfirstlane_b32 s30, v164
	v_and_b32_e32 v165, 63, v252
	v_lshlrev_b32_e32 v165, 4, v165
	s_barrier
	s_and_b32 s9, s8, 0x10000
	v_add_u32_e32 v221, s9, v218
	v_or_b32_e32 v226, s9, v219
	s_xor_b32 s9, s9, 0x10000
	s_add_u32 s9, s9, s30
	.p2align	6
